# phase E q-row loop: second head-group's 8 row loads issued with the first group's (one memory round trip per row instead of two), on top of RKP prefetch
# baseline (speedup 1.0000x reference)
.LBB0_774:
	s_mul_i32 s78, s3, 0xc0
	s_waitcnt lgkmcnt(0)
	s_cmp_lg_u32 s3, 0
	s_cbranch_scc1 .Lerow_second
	v_mov_b32_e32 v8, 0
	v_mov_b32_e32 v9, 0
	v_mov_b32_e32 v44, 0
	v_mov_b32_e32 v45, 0
	v_mov_b32_e32 v48, 0
	v_mov_b32_e32 v49, 0
	v_mov_b32_e32 v52, 0
	v_mov_b32_e32 v53, 0
	v_mov_b32_e32 v56, 0
	v_mov_b32_e32 v57, 0
	v_mov_b32_e32 v60, 0
	v_mov_b32_e32 v61, 0
	v_mov_b32_e32 v64, 0
	v_mov_b32_e32 v65, 0
	v_mov_b32_e32 v70, 0
	v_mov_b32_e32 v71, 0
	v_mov_b32_e32 v100, 0
	v_mov_b32_e32 v101, 0
	v_mov_b32_e32 v102, 0
	v_mov_b32_e32 v103, 0
	v_mov_b32_e32 v104, 0
	v_mov_b32_e32 v105, 0
	v_mov_b32_e32 v106, 0
	v_mov_b32_e32 v107, 0
	v_mov_b32_e32 v108, 0
	v_mov_b32_e32 v109, 0
	v_mov_b32_e32 v110, 0
	v_mov_b32_e32 v111, 0
	v_mov_b32_e32 v112, 0
	v_mov_b32_e32 v113, 0
	v_mov_b32_e32 v114, 0
	v_mov_b32_e32 v115, 0
	s_and_saveexec_b64 s[24:25], s[42:43]
	s_cbranch_execz .Lerow_ld_done
	v_lshl_add_u64 v[46:47], s[78:79], 1, v[40:41]
	global_load_dwordx2 v[8:9], v[46:47], off
	global_load_dwordx2 v[44:45], v[46:47], off offset:384
	global_load_dwordx2 v[64:65], v[46:47], off offset:768
	global_load_dwordx2 v[60:61], v[46:47], off offset:1152
	global_load_dwordx2 v[56:57], v[46:47], off offset:1536
	global_load_dwordx2 v[52:53], v[46:47], off offset:1920
	global_load_dwordx2 v[48:49], v[46:47], off offset:2304
	global_load_dwordx2 v[70:71], v[46:47], off offset:2688
	s_movk_i32 s78, 0x600
	v_lshl_add_u64 v[116:117], s[78:79], 1, v[40:41]
	s_mov_b32 s78, 0
	global_load_dwordx2 v[100:101], v[116:117], off
	global_load_dwordx2 v[102:103], v[116:117], off offset:384
	global_load_dwordx2 v[104:105], v[116:117], off offset:768
	global_load_dwordx2 v[106:107], v[116:117], off offset:1152
	global_load_dwordx2 v[108:109], v[116:117], off offset:1536
	global_load_dwordx2 v[110:111], v[116:117], off offset:1920
	global_load_dwordx2 v[112:113], v[116:117], off offset:2304
	global_load_dwordx2 v[114:115], v[116:117], off offset:2688
.Lerow_ld_done:
	s_or_b64 exec, exec, s[24:25]
	s_waitcnt vmcnt(0)
	s_branch .Lerow_compute
.Lerow_second:
	v_mov_b32_e32 v8, v100
	v_mov_b32_e32 v9, v101
	v_mov_b32_e32 v44, v102
	v_mov_b32_e32 v45, v103
	v_mov_b32_e32 v64, v104
	v_mov_b32_e32 v65, v105
	v_mov_b32_e32 v60, v106
	v_mov_b32_e32 v61, v107
	v_mov_b32_e32 v56, v108
	v_mov_b32_e32 v57, v109
	v_mov_b32_e32 v52, v110
	v_mov_b32_e32 v53, v111
	v_mov_b32_e32 v48, v112
	v_mov_b32_e32 v49, v113
	v_mov_b32_e32 v70, v114
	v_mov_b32_e32 v71, v115
.Lerow_compute:
	v_lshlrev_b32_e32 v46, 16, v48
	v_and_b32_e32 v47, 0xffff0000, v48
	v_lshlrev_b32_e32 v48, 16, v49
	v_and_b32_e32 v49, 0xffff0000, v49
	v_mul_f32_e32 v50, v47, v47
	v_mul_f32_e32 v51, v49, v49
	v_fmac_f32_e32 v50, v46, v46
	v_fmac_f32_e32 v51, v48, v48
	v_add_f32_e32 v82, v50, v51
	v_lshlrev_b32_e32 v50, 16, v52
	v_and_b32_e32 v51, 0xffff0000, v52
	v_lshlrev_b32_e32 v52, 16, v53
	v_and_b32_e32 v53, 0xffff0000, v53
	v_mul_f32_e32 v54, v51, v51
	v_mul_f32_e32 v55, v53, v53
	v_fmac_f32_e32 v54, v50, v50
	v_fmac_f32_e32 v55, v52, v52
	v_add_f32_e32 v83, v54, v55
	v_lshlrev_b32_e32 v54, 16, v56
	v_and_b32_e32 v55, 0xffff0000, v56
	v_lshlrev_b32_e32 v56, 16, v57
	v_and_b32_e32 v57, 0xffff0000, v57
	v_mul_f32_e32 v58, v55, v55
	v_mul_f32_e32 v59, v57, v57
	v_fmac_f32_e32 v58, v54, v54
	v_fmac_f32_e32 v59, v56, v56
	v_add_f32_e32 v84, v58, v59
	v_lshlrev_b32_e32 v58, 16, v60
	v_and_b32_e32 v59, 0xffff0000, v60
	v_lshlrev_b32_e32 v60, 16, v61
	v_and_b32_e32 v61, 0xffff0000, v61
	v_mul_f32_e32 v62, v59, v59
	v_mul_f32_e32 v63, v61, v61
	v_fmac_f32_e32 v62, v58, v58
	v_fmac_f32_e32 v63, v60, v60
	v_add_f32_e32 v85, v62, v63
	v_lshlrev_b32_e32 v62, 16, v64
	v_and_b32_e32 v63, 0xffff0000, v64
	v_lshlrev_b32_e32 v64, 16, v65
	v_and_b32_e32 v65, 0xffff0000, v65
	v_mul_f32_e32 v66, v63, v63
	v_mul_f32_e32 v67, v65, v65
	v_fmac_f32_e32 v66, v62, v62
	v_fmac_f32_e32 v67, v64, v64
	v_and_b32_e32 v73, 0xffff0000, v8
	v_and_b32_e32 v75, 0xffff0000, v9
	v_add_f32_e32 v86, v66, v67
	v_and_b32_e32 v67, 0xffff0000, v44
	v_and_b32_e32 v69, 0xffff0000, v45
	v_lshlrev_b32_e32 v72, 16, v8
	v_lshlrev_b32_e32 v74, 16, v9
	v_mul_f32_e32 v8, v73, v73
	v_mul_f32_e32 v9, v75, v75
	v_lshlrev_b32_e32 v66, 16, v44
	v_lshlrev_b32_e32 v68, 16, v45
	v_mul_f32_e32 v44, v67, v67
	v_mul_f32_e32 v45, v69, v69
	v_fmac_f32_e32 v8, v72, v72
	v_fmac_f32_e32 v9, v74, v74
	v_fmac_f32_e32 v44, v66, v66
	v_fmac_f32_e32 v45, v68, v68
	v_add_f32_e32 v88, v8, v9
	v_add_f32_e32 v87, v44, v45
	v_lshlrev_b32_e32 v44, 16, v71
	v_and_b32_e32 v45, 0xffff0000, v71
	ds_bpermute_b32 v71, v77, v88
	v_and_b32_e32 v9, 0xffff0000, v70
	v_lshlrev_b32_e32 v8, 16, v70
	v_mul_f32_e32 v70, v9, v9
	v_mul_f32_e32 v89, v45, v45
	v_fmac_f32_e32 v70, v8, v8
	v_fmac_f32_e32 v89, v44, v44
	v_add_f32_e32 v70, v70, v89
	s_waitcnt lgkmcnt(0)
	v_add_f32_e32 v71, v88, v71
	ds_bpermute_b32 v88, v77, v87
	ds_bpermute_b32 v89, v77, v86
	ds_bpermute_b32 v90, v77, v85
	ds_bpermute_b32 v91, v77, v84
	ds_bpermute_b32 v92, v77, v83
	s_waitcnt lgkmcnt(4)
	v_add_f32_e32 v87, v87, v88
	s_waitcnt lgkmcnt(3)
	v_add_f32_e32 v86, v86, v89
	ds_bpermute_b32 v88, v77, v82
	ds_bpermute_b32 v89, v77, v70
	s_waitcnt lgkmcnt(4)
	v_add_f32_e32 v85, v85, v90
	s_waitcnt lgkmcnt(3)
	v_add_f32_e32 v84, v84, v91
	ds_bpermute_b32 v90, v78, v71
	ds_bpermute_b32 v91, v78, v87
	s_waitcnt lgkmcnt(4)
	v_add_f32_e32 v83, v83, v92
	ds_bpermute_b32 v92, v78, v86
	s_waitcnt lgkmcnt(4)
	v_add_f32_e32 v82, v82, v88
	s_waitcnt lgkmcnt(3)
	v_add_f32_e32 v70, v70, v89
	ds_bpermute_b32 v88, v78, v85
	ds_bpermute_b32 v89, v78, v84
	s_waitcnt lgkmcnt(4)
	v_add_f32_e32 v71, v71, v90
	s_waitcnt lgkmcnt(3)
	v_add_f32_e32 v87, v87, v91
	ds_bpermute_b32 v90, v78, v83
	ds_bpermute_b32 v91, v78, v82
	s_waitcnt lgkmcnt(4)
	v_add_f32_e32 v86, v86, v92
	ds_bpermute_b32 v92, v78, v70
	s_waitcnt lgkmcnt(4)
	v_add_f32_e32 v85, v85, v88
	s_waitcnt lgkmcnt(3)
	v_add_f32_e32 v84, v84, v89
	ds_bpermute_b32 v88, v79, v71
	ds_bpermute_b32 v89, v79, v87
	s_waitcnt lgkmcnt(4)
	v_add_f32_e32 v83, v83, v90
	s_waitcnt lgkmcnt(3)
	v_add_f32_e32 v82, v82, v91
	ds_bpermute_b32 v90, v79, v86
	ds_bpermute_b32 v91, v79, v85
	s_waitcnt lgkmcnt(4)
	v_add_f32_e32 v70, v70, v92
	ds_bpermute_b32 v92, v79, v84
	s_waitcnt lgkmcnt(4)
	v_add_f32_e32 v71, v71, v88
	s_waitcnt lgkmcnt(3)
	v_add_f32_e32 v87, v87, v89
	ds_bpermute_b32 v88, v79, v83
	ds_bpermute_b32 v89, v79, v82
	s_waitcnt lgkmcnt(4)
	v_add_f32_e32 v86, v86, v90
	s_waitcnt lgkmcnt(3)
	v_add_f32_e32 v85, v85, v91
	ds_bpermute_b32 v90, v79, v70
	ds_bpermute_b32 v91, v76, v71
	s_waitcnt lgkmcnt(4)
	v_add_f32_e32 v84, v84, v92
	ds_bpermute_b32 v92, v76, v87
	s_waitcnt lgkmcnt(4)
	v_add_f32_e32 v83, v83, v88
	s_waitcnt lgkmcnt(3)
	v_add_f32_e32 v82, v82, v89
	ds_bpermute_b32 v88, v76, v86
	ds_bpermute_b32 v89, v76, v85
	s_waitcnt lgkmcnt(4)
	v_add_f32_e32 v70, v70, v90
	s_waitcnt lgkmcnt(3)
	v_add_f32_e32 v71, v71, v91
	ds_bpermute_b32 v90, v76, v84
	ds_bpermute_b32 v91, v76, v83
	s_waitcnt lgkmcnt(4)
	v_add_f32_e32 v87, v87, v92
	ds_bpermute_b32 v92, v76, v82
	s_waitcnt lgkmcnt(4)
	v_add_f32_e32 v86, v86, v88
	s_waitcnt lgkmcnt(3)
	v_add_f32_e32 v85, v85, v89
	ds_bpermute_b32 v88, v76, v70
	ds_bpermute_b32 v89, v80, v71
	s_waitcnt lgkmcnt(4)
	v_add_f32_e32 v84, v84, v90
	s_waitcnt lgkmcnt(3)
	v_add_f32_e32 v83, v83, v91
	ds_bpermute_b32 v90, v80, v87
	ds_bpermute_b32 v91, v80, v86
	ds_bpermute_b32 v93, v80, v85
	s_waitcnt lgkmcnt(5)
	v_add_f32_e32 v82, v82, v92
	s_waitcnt lgkmcnt(4)
	v_add_f32_e32 v70, v70, v88
	s_waitcnt lgkmcnt(3)
	v_add_f32_e32 v71, v71, v89
	s_waitcnt lgkmcnt(2)
	v_add_f32_e32 v94, v87, v90
	s_waitcnt lgkmcnt(1)
	v_add_f32_e32 v92, v86, v91
	s_waitcnt lgkmcnt(0)
	v_add_f32_e32 v90, v85, v93
	ds_bpermute_b32 v85, v80, v84
	ds_bpermute_b32 v87, v80, v82
	ds_bpermute_b32 v89, v80, v70
	ds_bpermute_b32 v91, v81, v71
	ds_bpermute_b32 v86, v80, v83
	s_waitcnt lgkmcnt(4)
	v_add_f32_e32 v88, v84, v85
	s_waitcnt lgkmcnt(3)
	v_add_f32_e32 v84, v82, v87
	s_waitcnt lgkmcnt(2)
	v_add_f32_e32 v82, v70, v89
	s_waitcnt lgkmcnt(1)
	v_add_f32_e32 v70, v71, v91
	v_fmamk_f32 v70, v70, 0x3baaaaab, v201
	v_mul_f32_e32 v71, 0x4f800000, v70
	v_cmp_gt_f32_e32 vcc, s91, v70
	s_waitcnt lgkmcnt(0)
	v_add_f32_e32 v86, v83, v86
	ds_bpermute_b32 v95, v81, v94
	v_cndmask_b32_e32 v70, v70, v71, vcc
	v_sqrt_f32_e32 v71, v70
	ds_bpermute_b32 v93, v81, v92
	ds_bpermute_b32 v91, v81, v90
	ds_bpermute_b32 v89, v81, v88
	v_add_u32_e32 v83, -1, v71
	v_fma_f32 v85, -v83, v71, v70
	v_cmp_ge_f32_e64 s[46:47], 0, v85
	v_add_u32_e32 v85, 1, v71
	ds_bpermute_b32 v87, v81, v86
	v_cndmask_b32_e64 v83, v71, v83, s[46:47]
	v_fma_f32 v71, -v85, v71, v70
	v_cmp_lt_f32_e64 s[46:47], 0, v71
	s_nop 1
	v_cndmask_b32_e64 v71, v83, v85, s[46:47]
	v_mul_f32_e32 v83, 0x37800000, v71
	v_cndmask_b32_e32 v71, v71, v83, vcc
	v_cmp_class_f32_e32 vcc, v70, v202
	ds_bpermute_b32 v85, v81, v84
	ds_bpermute_b32 v83, v81, v82
	v_cndmask_b32_e32 v70, v71, v70, vcc
	v_div_scale_f32 v71, s[4:5], v70, v70, 1.0
	v_rcp_f32_e32 v96, v71
	s_nop 0
	v_fma_f32 v97, -v71, v96, 1.0
	v_fmac_f32_e32 v96, v97, v96
	v_div_scale_f32 v97, vcc, 1.0, v70, 1.0
	v_mul_f32_e32 v98, v97, v96
	v_fma_f32 v99, -v71, v98, v97
	v_fmac_f32_e32 v98, v99, v96
	v_fma_f32 v71, -v71, v98, v97
	v_div_fmas_f32 v71, v71, v96, v98
	v_div_fixup_f32 v70, v71, v70, 1.0
	v_pk_mul_f32 v[74:75], v[74:75], v[70:71] op_sel_hi:[1,0]
	v_pk_mul_f32 v[70:71], v[72:73], v[70:71] op_sel_hi:[1,0]
	v_pk_mul_f32 v[72:73], v[12:13], v[74:75]
	v_pk_mul_f32 v[70:71], v[14:15], v[70:71]
	ds_bpermute_b32 v74, v76, v70
	ds_bpermute_b32 v75, v76, v71
	ds_bpermute_b32 v97, v76, v72
	ds_bpermute_b32 v96, v76, v73
	s_and_saveexec_b64 s[24:25], s[44:45]
	s_cbranch_execz .LBB0_792
	s_waitcnt lgkmcnt(1)
	v_mul_f32_e32 v97, v24, v97
	v_mul_f32_e32 v98, v5, v97
	s_waitcnt lgkmcnt(0)
	v_mul_f32_e32 v97, v24, v96
	v_mov_b32_e32 v96, v73
	v_pk_mul_f32 v[74:75], v[24:25], v[74:75]
	v_pk_mul_f32 v[96:97], v[6:7], v[96:97]
	v_pk_mul_f32 v[74:75], v[10:11], v[74:75]
	v_mul_f32_e32 v72, v4, v72
	v_mov_b32_e32 v73, v96
	v_mov_b32_e32 v99, v97
	v_pk_fma_f32 v[70:71], v[42:43], v[70:71], v[74:75]
	v_pk_add_f32 v[72:73], v[72:73], v[98:99]
